# no store drain in front of the per-unit barriers of the attention and Hyena-conv loops (+ loader wave, 4-buffer ring)
# speedup vs baseline: 1.0082x; 1.0082x over previous
.LBB0_709:
	s_bfe_u32 s10, s31, 0x30002
	s_lshl_b32 s1, s10, 2
	s_add_i32 s1, s18, s1
	v_med3_i32 v0, s1, 4, 28
	s_cmpk_gt_i32 s19, 0x1ff
	v_readfirstlane_b32 s1, v0
	s_mov_b64 s[2:3], -1
	s_barrier
	s_cbranch_scc0 .LBB0_732
	s_add_i32 s2, s19, 0xfffffe00
	s_lshr_b32 s14, s2, 7
	s_lshl_b32 s2, s19, 2
	s_and_b32 s11, s2, 28
	s_lshl_b32 s8, s14, 11
	s_add_i32 s2, s11, s18
	s_addk_i32 s8, 0x2000
	v_med3_i32 v4, s2, 4, 28
	s_lshl_b32 s2, s2, 6
	s_add_i32 s2, s8, s2
	v_or_b32_e32 v163, s2, v164
	v_mov_b64_e32 v[2:3], s[4:5]
	s_bfe_u32 s9, s19, 0x40003
	v_mad_i64_i32 v[2:3], s[2:3], v163, s29, v[2:3]
	s_lshl_b32 s20, s9, 6
	s_lshl_b32 s16, s9, 7
	s_add_i32 s2, s11, -4
	s_cmp_lg_u32 s11, 0
	s_mul_i32 s9, s8, 0x7c00
	v_med3_u32 v0, s11, 1, 25
	s_cselect_b32 s11, s2, 0
	s_mul_hi_u32 s3, s8, 0x7c00
	s_add_u32 s9, s4, s9
	v_readfirstlane_b32 s2, v4
	s_addc_u32 s3, s5, s3
	s_mul_i32 s2, s2, 0xf8000
	s_add_u32 s9, s9, s16
	v_lshl_add_u64 v[2:3], v[2:3], 0, s[16:17]
	s_addc_u32 s15, s3, 0
	s_add_i32 s16, s2, 0xffc20000
	s_lshl_b64 s[2:3], s[16:17], 1
	s_add_u32 s2, s9, s2
	v_lshl_add_u64 v[2:3], v[148:149], 1, v[2:3]
	s_addc_u32 s3, s15, s3
	global_load_dwordx4 v[66:69], v[2:3], off
	global_load_dwordx4 v[70:73], v[2:3], off offset:32
	global_load_dwordx4 v[74:77], v[2:3], off offset:64
	global_load_dwordx4 v[78:81], v[2:3], off offset:96
	v_lshl_add_u64 v[2:3], s[2:3], 0, v[150:151]
	v_lshl_add_u64 v[2:3], v[152:153], 1, v[2:3]
	global_load_dwordx4 v[82:85], v[2:3], off offset:2048
	global_load_dwordx4 v[86:89], v[2:3], off offset:2080
	global_load_dwordx4 v[90:93], v[2:3], off offset:2112
	global_load_dwordx4 v[94:97], v[2:3], off offset:2144
	v_add_co_u32_e32 v2, vcc, 0xf8000, v2
	v_subrev_u32_e32 v0, s11, v0
	s_nop 0
	v_addc_co_u32_e32 v3, vcc, 0, v3, vcc
	global_load_dwordx4 v[98:101], v[2:3], off offset:2048
	global_load_dwordx4 v[102:105], v[2:3], off offset:2080
	global_load_dwordx4 v[106:109], v[2:3], off offset:2112
	global_load_dwordx4 v[110:113], v[2:3], off offset:2144
	v_lshlrev_b32_e32 v0, 9, v0
	v_add_u32_e32 v2, 0xe00, v0
	s_lshl_b32 s15, s11, 6
	s_add_i32 s15, s15, s8
	v_readfirstlane_b32 s32, v2
	v_ashrrev_i32_e32 v8, 3, v146
	v_mov_b64_e32 v[4:5], s[4:5]
	v_add_u32_e32 v6, s15, v8
	s_lshl_b32 s16, s20, 1
	v_mad_i64_i32 v[4:5], s[24:25], v6, s29, v[4:5]
	v_lshlrev_b32_e32 v0, 1, v156
	v_lshl_add_u64 v[4:5], v[4:5], 0, s[16:17]
	v_lshl_add_u64 v[4:5], v[4:5], 0, v[0:1]
	v_add_co_u32_e32 v4, vcc, 0x1000, v4
	s_mov_b64 s[8:9], 0x1f0000
	s_nop 0
	v_addc_co_u32_e32 v5, vcc, 0, v5, vcc
	global_load_dwordx4 v[180:183], v[4:5], off
	v_lshl_add_u64 v[4:5], v[4:5], 0, s[8:9]
	global_load_dwordx4 v[184:187], v[4:5], off
	v_lshl_add_u64 v[4:5], v[4:5], 0, s[8:9]
	global_load_dwordx4 v[188:191], v[4:5], off
	v_lshl_add_u64 v[4:5], v[4:5], 0, s[8:9]
	global_load_dwordx4 v[192:195], v[4:5], off
	v_lshl_add_u64 v[4:5], v[4:5], 0, s[8:9]
	global_load_dwordx4 v[196:199], v[4:5], off
	v_lshl_add_u64 v[4:5], v[4:5], 0, s[8:9]
	global_load_dwordx4 v[200:203], v[4:5], off
	v_lshl_add_u64 v[4:5], v[4:5], 0, s[8:9]
	global_load_dwordx4 v[204:207], v[4:5], off
	v_lshl_add_u64 v[4:5], v[4:5], 0, s[8:9]
	global_load_dwordx4 v[208:211], v[4:5], off
	s_cmpk_lt_u32 s32, 0x1200
	s_cbranch_scc1 .Latt_lat_v_issued
	v_lshl_add_u64 v[4:5], v[4:5], 0, s[8:9]
	global_load_dwordx4 v[212:215], v[4:5], off
	s_cmpk_lt_u32 s32, 0x1400
	s_cbranch_scc1 .Latt_lat_v_issued
	v_lshl_add_u64 v[4:5], v[4:5], 0, s[8:9]
	global_load_dwordx4 v[216:219], v[4:5], off
	s_cmpk_lt_u32 s32, 0x1600
	s_cbranch_scc1 .Latt_lat_v_issued
	v_lshl_add_u64 v[4:5], v[4:5], 0, s[8:9]
	global_load_dwordx4 v[142:145], v[4:5], off

.LBB0_742:
	v_mov_b32_e32 v2, v234
	s_barrier
	s_lshl_b32 s5, s19, 3
	v_writelane_b32 v253, s8, 8
	s_add_i32 s10, s5, s62
	v_readlane_b32 s0, v253, 61
	v_writelane_b32 v253, s19, 7
	s_cmpk_gt_i32 s10, 0xfff
	v_mov_b32_e32 v0, s0
	v_readlane_b32 s0, v254, 5
	ds_read_b64 v[8:9], v0
	s_waitcnt lgkmcnt(0)
	v_readfirstlane_b32 s2, v8
	v_mov_b32_e32 v0, s0
	ds_read_b128 v[4:7], v0
	v_readfirstlane_b32 s3, v9
	s_waitcnt lgkmcnt(0)
	v_readfirstlane_b32 s1, v4
	v_readfirstlane_b32 s4, v5
	v_readfirstlane_b32 s0, v6
	v_readfirstlane_b32 s5, v7
	s_cbranch_scc1 .LBB0_796
	v_readlane_b32 s6, v253, 8
	v_readlane_b32 s12, v254, 60
	s_lshl_b32 s11, s6, 3
	s_mul_i32 s7, s12, 0x9000
	s_mul_hi_u32 s6, s12, 0x9000
	s_add_u32 s1, s1, s7
	s_addc_u32 s8, s4, s6
	s_lshl_b32 s4, s62, 14
	s_add_i32 s9, s4, 0
	s_mul_i32 s6, s12, 0x3000
	s_mul_hi_u32 s4, s12, 0x3000
	s_add_u32 s0, s0, s6
	s_addc_u32 s7, s5, s4
	s_add_u32 s4, s0, 0x1000
	v_lshlrev_b32_e32 v0, 2, v2
	s_addc_u32 s5, s7, 0
	v_lshlrev_b32_e32 v3, 3, v2
	v_and_b32_e32 v136, 60, v0
	s_add_u32 s6, s0, 0x2000
	v_mov_b32_e32 v0, s9
	v_and_b32_e32 v3, 56, v3
	s_movk_i32 s0, 0x88
	v_readlane_b32 s13, v254, 61
	v_mad_u32_u24 v6, v3, s0, v0
	v_lshlrev_b32_e32 v0, 1, v3
	s_addc_u32 s7, s7, 0
	v_lshl_add_u64 v[4:5], s[2:3], 0, v[0:1]
	s_mov_b64 s[12:13], 0x70800000
	v_lshl_add_u64 v[36:37], v[4:5], 0, s[12:13]
	s_add_u32 s12, s1, 0x1000
	s_addc_u32 s13, s8, 0
	s_add_u32 s20, s1, 0x2000
	s_addc_u32 s21, s8, 0
	v_add_u32_e32 v0, 64, v2
	s_add_u32 s34, s1, 0x4000
	v_ashrrev_i32_e32 v139, 3, v0
	v_add_u32_e32 v0, 0x80, v2
	s_addc_u32 s35, s8, 0
	v_ashrrev_i32_e32 v141, 3, v0
	v_add_u32_e32 v0, 0xc0, v2
	s_add_u32 s36, s1, 0x5000
	v_ashrrev_i32_e32 v143, 3, v0
	v_add_u32_e32 v0, 0x100, v2
	s_addc_u32 s37, s8, 0
	v_ashrrev_i32_e32 v145, 3, v0
	v_add_u32_e32 v0, 0x140, v2
	s_add_u32 s38, s1, 0x7000
	v_ashrrev_i32_e32 v147, 3, v0
	v_add_u32_e32 v0, 0x180, v2
	s_addc_u32 s39, s8, 0
	v_ashrrev_i32_e32 v149, 3, v0
	v_add_u32_e32 v0, 0x1c0, v2
	v_ashrrev_i32_e32 v137, 3, v2
	s_add_u32 s40, s1, 0x8000
	v_ashrrev_i32_e32 v151, 3, v0
	v_ashrrev_i32_e32 v35, 4, v2
	v_lshl_add_u32 v34, v136, 1, s9
	v_lshl_add_u32 v138, v137, 1, v6
	s_addc_u32 s41, s8, 0
	v_lshl_add_u32 v140, v139, 1, v6
	v_lshl_add_u32 v142, v141, 1, v6
	v_lshl_add_u32 v144, v143, 1, v6
	v_lshl_add_u32 v146, v145, 1, v6
	v_lshl_add_u32 v148, v147, 1, v6
	v_lshl_add_u32 v150, v149, 1, v6
	v_lshl_add_u32 v152, v151, 1, v6
	s_branch .LBB0_745

.LBB0_900:
	s_cmpk_lt_i32 s25, 0x400
	s_cselect_b64 s[8:9], -1, 0
	s_and_b32 s26, s25, 0x3ff
	s_cmpk_gt_i32 s25, 0x3ff
	s_cselect_b64 s[6:7], -1, 0
	s_and_b64 s[12:13], s[6:7], exec
	s_movk_i32 s12, 0x148
	s_cselect_b32 s27, s12, 0x848
	s_movk_i32 s12, 0x290
	s_cselect_b32 s28, s12, 0x1090
	s_mov_b32 s12, 0x70500000
	s_cselect_b32 s30, s12, 0x6f400000
	s_lshr_b32 s16, s27, 3
	v_cmp_gt_i32_e32 vcc, s16, v22
	s_barrier
	s_mov_b64 s[42:43], vcc
	s_and_saveexec_b64 s[12:13], vcc
	s_cbranch_execz .LBB0_903
	s_or_b32 s14, s4, s26
	s_add_u32 s15, s2, s30
	s_mul_i32 s21, s5, s28
	s_mul_hi_u32 s29, s14, s28
	s_addc_u32 s20, s3, 0
	s_add_i32 s29, s29, s21
	s_mul_i32 s14, s14, s28
	s_add_u32 s14, s15, s14
	s_addc_u32 s15, s20, s29
	v_mov_b32_e32 v2, v32
	v_ashrrev_i32_e32 v3, 31, v2
	v_lshl_add_u64 v[6:7], v[2:3], 1, s[14:15]
	global_load_dwordx4 v[118:121], v[6:7], off
